# baseline (speedup 1.0000x reference)
; template <int TRM>
; DI void inproj_epi(const acc4 (&acc)[2][2][4][2], int wr, int wc, int fr, int fq, int pm, int pn, u16* R, u16* T, float* CB, u32* KMAX2, const float* bfp, char* lds) {
;     ...
; #pragma unroll
;               for (int ai = 0; ai < 2; ++ai)
; #pragma unroll
;                 for (int m = 0; m < 4; ++m) {
;                   const int tok = pm * 256 + ai * 128 + wr * 64 + m * 16 + fq * 4;
; #pragma unroll
;                   for (int n = 0; n < 2; ++n) {
;                     const int trow = cbase + n * 16 + fr - LDR;
;                     const acc4 v = acc[ai][bj][m][n];
;                     const u32 p01 = pack2(v[0], v[1]), p23 = pack2(v[2], v[3]);
;                     u32x2 pk = {p01, p23};
;                     *reinterpret_cast<u32x2*>(T + (trow * SEQ + tok)) = pk;
;                   }
;                   __builtin_amdgcn_sched_barrier(0);
;                 }
.LBB0_238:
	v_readlane_b32 s14, v255, 52
	s_lshl_b32 s10, s14, 8
	s_lshl_b32 s11, s11, 5
	s_or_b32 s10, s11, s10
	v_or_b32_e32 v131, s10, v0
	s_add_i32 s10, s22, s12
	s_add_i32 s12, s10, 0xfde00000
	v_lshl_or_b32 v132, v130, 2, s12
	v_lshlrev_b32_e32 v131, 14, v131
	v_cvt_pk_bf16_f32 v126, v126, v127
	v_cvt_pk_bf16_f32 v127, v128, v129
	v_add_u32_e32 v128, v131, v132
	v_readlane_b32 s12, v252, 56
	v_ashrrev_i32_e32 v129, 31, v128
	v_readlane_b32 s13, v252, 57
	v_cvt_pk_bf16_f32 v122, v122, v123
	v_cvt_pk_bf16_f32 v123, v124, v125
	v_lshl_add_u64 v[128:129], v[128:129], 1, s[12:13]
	global_store_dwordx2 v[128:129], v[126:127], off
	v_or_b32_e32 v128, 0x40000, v131
	v_add_u32_e32 v124, v128, v132
	v_ashrrev_i32_e32 v125, 31, v124
	v_lshl_add_u64 v[124:125], v[124:125], 1, s[12:13]
	global_store_dwordx2 v[124:125], v[122:123], off
	v_or_b32_e32 v124, 16, v132
	v_cvt_pk_bf16_f32 v118, v118, v119
	v_cvt_pk_bf16_f32 v119, v120, v121
	v_add_u32_e32 v120, v131, v124
	v_cvt_pk_bf16_f32 v114, v114, v115
	v_cvt_pk_bf16_f32 v115, v116, v117
	v_add_u32_e32 v116, v128, v124
	v_ashrrev_i32_e32 v121, 31, v120
	v_ashrrev_i32_e32 v117, 31, v116
	v_lshl_add_u64 v[120:121], v[120:121], 1, s[12:13]
	v_lshl_add_u64 v[116:117], v[116:117], 1, s[12:13]
	global_store_dwordx2 v[120:121], v[118:119], off
	global_store_dwordx2 v[116:117], v[114:115], off
	v_or_b32_e32 v116, 32, v132
	v_cvt_pk_bf16_f32 v106, v106, v107
	v_cvt_pk_bf16_f32 v107, v108, v109
	v_add_u32_e32 v108, v131, v116
	v_cvt_pk_bf16_f32 v98, v98, v99
	v_cvt_pk_bf16_f32 v99, v100, v101
	v_add_u32_e32 v100, v128, v116
	v_ashrrev_i32_e32 v109, 31, v108
	v_ashrrev_i32_e32 v101, 31, v100
	v_lshl_add_u64 v[108:109], v[108:109], 1, s[12:13]
	v_lshl_add_u64 v[100:101], v[100:101], 1, s[12:13]
	global_store_dwordx2 v[108:109], v[106:107], off
	global_store_dwordx2 v[100:101], v[98:99], off
	v_or_b32_e32 v117, 48, v132
	v_cvt_pk_bf16_f32 v108, v90, v91
	v_add_u32_e32 v90, v131, v117
	v_cvt_pk_bf16_f32 v100, v82, v83
	v_add_u32_e32 v82, v128, v117
	v_ashrrev_i32_e32 v91, 31, v90
	v_ashrrev_i32_e32 v83, 31, v82
	v_cvt_pk_bf16_f32 v109, v92, v93
	v_lshl_add_u64 v[90:91], v[90:91], 1, s[12:13]
	v_cvt_pk_bf16_f32 v101, v84, v85
	v_lshl_add_u64 v[82:83], v[82:83], 1, s[12:13]
	global_store_dwordx2 v[90:91], v[108:109], off
	global_store_dwordx2 v[82:83], v[100:101], off
	v_add_u32_e32 v120, 0x80, v132
	v_add_u32_e32 v82, v131, v120
	v_ashrrev_i32_e32 v83, 31, v82
	v_add_u32_e32 v84, v128, v120
	v_cvt_pk_bf16_f32 v90, v110, v111
	v_cvt_pk_bf16_f32 v91, v112, v113
	v_lshl_add_u64 v[82:83], v[82:83], 1, s[12:13]
	v_ashrrev_i32_e32 v85, 31, v84
	global_store_dwordx2 v[82:83], v[90:91], off
	v_cvt_pk_bf16_f32 v82, v102, v103
	v_cvt_pk_bf16_f32 v83, v104, v105
	v_lshl_add_u64 v[84:85], v[84:85], 1, s[12:13]
	global_store_dwordx2 v[84:85], v[82:83], off
	v_add_u32_e32 v102, 0x90, v132
	v_add_u32_e32 v84, v131, v102
	v_ashrrev_i32_e32 v85, 31, v84
	v_cvt_pk_bf16_f32 v92, v94, v95
	v_cvt_pk_bf16_f32 v93, v96, v97
	v_lshl_add_u64 v[84:85], v[84:85], 1, s[12:13]
	global_store_dwordx2 v[84:85], v[92:93], off
	v_cvt_pk_bf16_f32 v84, v86, v87
	v_add_u32_e32 v86, v128, v102
	v_ashrrev_i32_e32 v87, 31, v86
	v_cvt_pk_bf16_f32 v85, v88, v89
	v_lshl_add_u64 v[86:87], v[86:87], 1, s[12:13]
	global_store_dwordx2 v[86:87], v[84:85], off
	v_add_u32_e32 v86, 0xa0, v132
	v_cvt_pk_bf16_f32 v78, v78, v79
	v_cvt_pk_bf16_f32 v79, v80, v81
	v_add_u32_e32 v80, v131, v86
	v_cvt_pk_bf16_f32 v74, v74, v75
	v_cvt_pk_bf16_f32 v75, v76, v77
	v_add_u32_e32 v76, v128, v86
	v_ashrrev_i32_e32 v81, 31, v80
	v_ashrrev_i32_e32 v77, 31, v76
	v_lshl_add_u64 v[80:81], v[80:81], 1, s[12:13]
	v_lshl_add_u64 v[76:77], v[76:77], 1, s[12:13]
	global_store_dwordx2 v[80:81], v[78:79], off
	global_store_dwordx2 v[76:77], v[74:75], off
	v_add_u32_e32 v76, 0xb0, v132
	v_cvt_pk_bf16_f32 v70, v70, v71
	v_cvt_pk_bf16_f32 v71, v72, v73
	v_add_u32_e32 v72, v131, v76
	v_cvt_pk_bf16_f32 v66, v66, v67
	v_cvt_pk_bf16_f32 v67, v68, v69
	v_add_u32_e32 v68, v128, v76
	v_ashrrev_i32_e32 v73, 31, v72
	v_ashrrev_i32_e32 v69, 31, v68
	v_lshl_add_u64 v[72:73], v[72:73], 1, s[12:13]
	v_lshl_add_u64 v[68:69], v[68:69], 1, s[12:13]
	global_store_dwordx2 v[72:73], v[70:71], off
	global_store_dwordx2 v[68:69], v[66:67], off
	v_or_b32_e32 v68, 0x200000, v131
	v_cvt_pk_bf16_f32 v62, v62, v63
	v_cvt_pk_bf16_f32 v63, v64, v65
	v_add_u32_e32 v64, v68, v132
	v_ashrrev_i32_e32 v65, 31, v64
	v_lshl_add_u64 v[64:65], v[64:65], 1, s[12:13]
	global_store_dwordx2 v[64:65], v[62:63], off
	v_or_b32_e32 v64, 0x240000, v131
	v_cvt_pk_bf16_f32 v58, v58, v59
	v_cvt_pk_bf16_f32 v59, v60, v61
	v_add_u32_e32 v60, v64, v132
	v_ashrrev_i32_e32 v61, 31, v60
	v_lshl_add_u64 v[60:61], v[60:61], 1, s[12:13]
	global_store_dwordx2 v[60:61], v[58:59], off
	v_cvt_pk_bf16_f32 v54, v54, v55
	v_cvt_pk_bf16_f32 v55, v56, v57
	v_add_u32_e32 v56, v68, v124
	v_cvt_pk_bf16_f32 v50, v50, v51
	v_cvt_pk_bf16_f32 v51, v52, v53
	v_add_u32_e32 v52, v64, v124
	v_ashrrev_i32_e32 v57, 31, v56
	v_ashrrev_i32_e32 v53, 31, v52
	v_lshl_add_u64 v[56:57], v[56:57], 1, s[12:13]
	v_lshl_add_u64 v[52:53], v[52:53], 1, s[12:13]
	global_store_dwordx2 v[56:57], v[54:55], off
	global_store_dwordx2 v[52:53], v[50:51], off
	v_cvt_pk_bf16_f32 v46, v46, v47
	v_cvt_pk_bf16_f32 v47, v48, v49
	v_add_u32_e32 v48, v68, v116
	v_cvt_pk_bf16_f32 v38, v38, v39
	v_cvt_pk_bf16_f32 v39, v40, v41
	v_add_u32_e32 v40, v64, v116
	v_ashrrev_i32_e32 v49, 31, v48
	v_ashrrev_i32_e32 v41, 31, v40
	v_lshl_add_u64 v[48:49], v[48:49], 1, s[12:13]
	v_lshl_add_u64 v[40:41], v[40:41], 1, s[12:13]
	global_store_dwordx2 v[48:49], v[46:47], off
	global_store_dwordx2 v[40:41], v[38:39], off
; template <int TRM>
; DI void inproj_epi(const acc4 (&acc)[2][2][4][2], int wr, int wc, int fr, int fq, int pm, int pn, u16* R, u16* T, float* CB, u32* KMAX2, const float* bfp, char* lds) {
;     ...
;   if (TRM == 0 && pn == 9) {
;     int tx = (int)threadIdx.x;
;     asm volatile("" : "+v"(tx));
;     u16* sT = reinterpret_cast<u16*>(lds);
; #pragma unroll
;     for (int bj = 0; bj < 2; ++bj)
; #pragma unroll
;       for (int ai = 0; ai < 2; ++ai)
; #pragma unroll
;         for (int n = 0; n < 2; ++n) {
;           const int cl = bj * 128 + wc * 32 + n * 16 + fr;
;           u32 pk01[4], pk23[4];
; #pragma unroll
;           for (int m = 0; m < 4; ++m) {
;             const acc4 v = acc[ai][bj][m][n];
;             pk01[m] = pack2(v[0], v[1]); pk23[m] = pack2(v[2], v[3]);
;             const int tl = ai * 128 + wr * 64 + m * 16 + fq * 4;
;             u32x2 w = {pk01[m], pk23[m]};
;             *reinterpret_cast<u32x2*>(sT + cl * 256 + tl) = w;
;           }
;           const int p16 = (pm * 256 + ai * 128 + wr * 64) >> 4;
;           u16* t16 = T + (size_t)(TR_VB16 + cl) * SEQ + p16;
;           u32x2 w0 = {(pk01[0] & 0xffffu) | (pk01[1] << 16), (pk01[2] & 0xffffu) | (pk01[3] << 16)};
;           u32x2 w1 = {(pk01[0] >> 16) | (pk01[1] & 0xffff0000u), (pk01[2] >> 16) | (pk01[3] & 0xffff0000u)};
;           u32x2 w2 = {(pk23[0] & 0xffffu) | (pk23[1] << 16), (pk23[2] & 0xffffu) | (pk23[3] << 16)};
;           u32x2 w3 = {(pk23[0] >> 16) | (pk23[1] & 0xffff0000u), (pk23[2] >> 16) | (pk23[3] & 0xffff0000u)};
;           *reinterpret_cast<u32x2*>(t16 + (fq * 4 + 0) * (SEQ / 16)) = w0;
;           *reinterpret_cast<u32x2*>(t16 + (fq * 4 + 1) * (SEQ / 16)) = w1;
;           *reinterpret_cast<u32x2*>(t16 + (fq * 4 + 2) * (SEQ / 16)) = w2;
;           *reinterpret_cast<u32x2*>(t16 + (fq * 4 + 3) * (SEQ / 16)) = w3;
	v_cvt_pk_bf16_f32 v40, v30, v31
	v_add_u32_e32 v30, v68, v117
	v_ashrrev_i32_e32 v31, 31, v30
	v_cvt_pk_bf16_f32 v41, v32, v33
	v_lshl_add_u64 v[30:31], v[30:31], 1, s[12:13]
	global_store_dwordx2 v[30:31], v[40:41], off
	v_cvt_pk_bf16_f32 v30, v22, v23
	v_add_u32_e32 v22, v64, v117
	v_ashrrev_i32_e32 v23, 31, v22
	v_cvt_pk_bf16_f32 v31, v24, v25
	v_lshl_add_u64 v[22:23], v[22:23], 1, s[12:13]
	global_store_dwordx2 v[22:23], v[30:31], off
	v_add_u32_e32 v22, v68, v120
	v_ashrrev_i32_e32 v23, 31, v22
	v_add_u32_e32 v32, v64, v120
	v_cvt_pk_bf16_f32 v24, v42, v43
	v_cvt_pk_bf16_f32 v25, v44, v45
	v_lshl_add_u64 v[22:23], v[22:23], 1, s[12:13]
	v_ashrrev_i32_e32 v33, 31, v32
	global_store_dwordx2 v[22:23], v[24:25], off
	v_cvt_pk_bf16_f32 v22, v34, v35
	v_cvt_pk_bf16_f32 v23, v36, v37
	v_lshl_add_u64 v[32:33], v[32:33], 1, s[12:13]
	global_store_dwordx2 v[32:33], v[22:23], off
	v_cvt_pk_bf16_f32 v26, v26, v27
	v_cvt_pk_bf16_f32 v27, v28, v29
	v_add_u32_e32 v28, v68, v102
	v_cvt_pk_bf16_f32 v18, v18, v19
	v_cvt_pk_bf16_f32 v19, v20, v21
	v_add_u32_e32 v20, v64, v102
	v_ashrrev_i32_e32 v29, 31, v28
	v_ashrrev_i32_e32 v21, 31, v20
	v_lshl_add_u64 v[28:29], v[28:29], 1, s[12:13]
	v_lshl_add_u64 v[20:21], v[20:21], 1, s[12:13]
	global_store_dwordx2 v[28:29], v[26:27], off
	global_store_dwordx2 v[20:21], v[18:19], off
	v_cvt_pk_bf16_f32 v14, v14, v15
	v_cvt_pk_bf16_f32 v15, v16, v17
	v_add_u32_e32 v16, v68, v86
	v_cvt_pk_bf16_f32 v10, v10, v11
	v_cvt_pk_bf16_f32 v11, v12, v13
	v_add_u32_e32 v12, v64, v86
	v_ashrrev_i32_e32 v17, 31, v16
	v_ashrrev_i32_e32 v13, 31, v12
	v_lshl_add_u64 v[16:17], v[16:17], 1, s[12:13]
	v_lshl_add_u64 v[12:13], v[12:13], 1, s[12:13]
	global_store_dwordx2 v[16:17], v[14:15], off
	global_store_dwordx2 v[12:13], v[10:11], off
	v_cvt_pk_bf16_f32 v6, v6, v7
	v_cvt_pk_bf16_f32 v7, v8, v9
	v_add_u32_e32 v8, v68, v76
	v_cvt_pk_bf16_f32 v2, v2, v3
	v_cvt_pk_bf16_f32 v3, v4, v5
	v_add_u32_e32 v4, v64, v76
	v_ashrrev_i32_e32 v9, 31, v8
	v_ashrrev_i32_e32 v5, 31, v4
	v_lshl_add_u64 v[8:9], v[8:9], 1, s[12:13]
	v_lshl_add_u64 v[4:5], v[4:5], 1, s[12:13]
	global_store_dwordx2 v[8:9], v[6:7], off
	global_store_dwordx2 v[4:5], v[2:3], off
	s_cmp_lg_u32 s14, 9
	s_cbranch_scc1 .LBB0_240
	s_lshl_b32 s12, s23, 7
	v_or_b32_e32 v36, s11, v0
	v_readlane_b32 s48, v252, 56
	s_add_i32 s12, s12, 16
	v_lshlrev_b32_e32 v0, 15, v36
	v_readlane_b32 s49, v252, 57
	v_lshl_add_u32 v5, v130, 3, s12
	s_ashr_i32 s12, s10, 4
	v_lshl_add_u64 v[8:9], s[48:49], 0, v[0:1]
	v_and_b32_e32 v0, 0xffff, v126
	s_ashr_i32 s13, s12, 31
	v_lshl_or_b32 v16, v118, 16, v0
	v_and_b32_e32 v0, 0xffff, v106
	s_lshl_b64 s[44:45], s[12:13], 1
	v_lshl_or_b32 v17, v108, 16, v0
	v_lshrrev_b32_e32 v0, 16, v126
	s_mov_b32 s13, 0xffff0000
	v_and_or_b32 v20, v118, s13, v0
	v_lshrrev_b32_e32 v0, 16, v106
	v_and_or_b32 v21, v108, s13, v0
	v_and_b32_e32 v0, 0xffff, v127
	v_lshl_or_b32 v28, v119, 16, v0
	v_and_b32_e32 v0, 0xffff, v107
	s_mov_b64 s[50:51], 0x2400000
	v_lshl_or_b32 v29, v109, 16, v0
	v_lshrrev_b32_e32 v0, 16, v127
	v_lshl_add_u64 v[8:9], v[8:9], 0, s[50:51]
	v_and_or_b32 v32, v119, s13, v0
	v_lshrrev_b32_e32 v0, 16, v107
	v_lshl_add_u64 v[12:13], v[8:9], 0, s[44:45]
	v_and_or_b32 v33, v109, s13, v0
	v_lshlrev_b32_e32 v0, 13, v130
	v_mov_b32_e32 v4, v159
	v_lshl_add_u32 v37, v36, 9, v5
	v_lshl_add_u64 v[12:13], v[12:13], 0, v[0:1]
	s_movk_i32 s12, 0x1000
	ds_write2_b64 v37, v[126:127], v[118:119] offset1:4
	ds_write2_b64 v37, v[106:107], v[108:109] offset0:8 offset1:12
	v_add_co_u32_e32 v12, vcc, s12, v12
	v_and_b32_e32 v20, 0xffff, v122
	s_nop 0
	v_addc_co_u32_e32 v13, vcc, 0, v13, vcc
	v_or_b32_e32 v12, 16, v36
	v_lshl_add_u32 v42, v12, 9, v5
	v_lshlrev_b32_e32 v12, 15, v12
	v_mov_b32_e32 v13, v1
	v_lshl_add_u64 v[12:13], s[48:49], 0, v[12:13]
	v_lshl_add_u64 v[12:13], v[12:13], 0, s[50:51]
	v_lshl_add_u64 v[16:17], v[12:13], 0, s[44:45]
	v_and_b32_e32 v21, 0xffff, v98
	s_addk_i32 s10, 0x80
	v_lshl_or_b32 v20, v114, 16, v20
	v_lshl_or_b32 v21, v100, 16, v21
	v_lshrrev_b32_e32 v28, 16, v122
	v_lshrrev_b32_e32 v29, 16, v98
	v_lshl_add_u64 v[16:17], v[16:17], 0, v[0:1]
	s_ashr_i32 s10, s10, 4
	ds_write2_b64 v42, v[122:123], v[114:115] offset1:4
	ds_write2_b64 v42, v[98:99], v[100:101] offset0:8 offset1:12
	v_and_or_b32 v28, v114, s13, v28
	v_and_or_b32 v29, v100, s13, v29
	v_and_b32_e32 v32, 0xffff, v123
	v_and_b32_e32 v33, 0xffff, v99
	v_add_co_u32_e32 v16, vcc, s12, v16
	s_ashr_i32 s11, s10, 31
	v_lshl_or_b32 v32, v115, 16, v32
	v_lshl_or_b32 v33, v101, 16, v33
	v_lshrrev_b32_e32 v34, 16, v123
	v_lshrrev_b32_e32 v35, 16, v99
	v_addc_co_u32_e32 v17, vcc, 0, v17, vcc
	s_lshl_b64 s[46:47], s[10:11], 1
	v_and_or_b32 v34, v115, s13, v34
	v_and_or_b32 v35, v101, s13, v35
	v_lshl_add_u64 v[8:9], v[8:9], 0, s[46:47]
	v_and_b32_e32 v16, 0xffff, v90
	v_and_b32_e32 v17, 0xffff, v78
	v_lshl_or_b32 v16, v92, 16, v16
	v_lshl_or_b32 v17, v70, 16, v17
	v_lshrrev_b32_e32 v20, 16, v90
	v_lshrrev_b32_e32 v21, 16, v78
	v_lshl_add_u64 v[8:9], v[8:9], 0, v[0:1]
	ds_write2_b64 v37, v[90:91], v[92:93] offset0:32 offset1:36
	ds_write2_b64 v37, v[78:79], v[70:71] offset0:40 offset1:44
	v_and_or_b32 v20, v92, s13, v20
	v_and_or_b32 v21, v70, s13, v21
	v_and_b32_e32 v28, 0xffff, v91
	v_and_b32_e32 v29, 0xffff, v79
	v_add_co_u32_e32 v8, vcc, s12, v8
	v_lshl_or_b32 v28, v93, 16, v28
	v_lshl_or_b32 v29, v71, 16, v29
	v_lshrrev_b32_e32 v32, 16, v91
	v_lshrrev_b32_e32 v33, 16, v79
	v_addc_co_u32_e32 v9, vcc, 0, v9, vcc
	v_and_or_b32 v32, v93, s13, v32
	v_and_or_b32 v33, v71, s13, v33
	v_lshl_add_u64 v[8:9], v[12:13], 0, s[46:47]
	v_and_b32_e32 v12, 0xffff, v82
	v_and_b32_e32 v13, 0xffff, v74
; template <int TRM>
; DI void inproj_epi(const acc4 (&acc)[2][2][4][2], int wr, int wc, int fr, int fq, int pm, int pn, u16* R, u16* T, float* CB, u32* KMAX2, const float* bfp, char* lds) {
;     ...
;           const int cl = bj * 128 + wc * 32 + n * 16 + fr;
;           u32 pk01[4], pk23[4];
; #pragma unroll
;           for (int m = 0; m < 4; ++m) {
;             const acc4 v = acc[ai][bj][m][n];
;             pk01[m] = pack2(v[0], v[1]); pk23[m] = pack2(v[2], v[3]);
;             const int tl = ai * 128 + wr * 64 + m * 16 + fq * 4;
;             u32x2 w = {pk01[m], pk23[m]};
;             *reinterpret_cast<u32x2*>(sT + cl * 256 + tl) = w;
;           }
;           const int p16 = (pm * 256 + ai * 128 + wr * 64) >> 4;
;           u16* t16 = T + (size_t)(TR_VB16 + cl) * SEQ + p16;
;           u32x2 w0 = {(pk01[0] & 0xffffu) | (pk01[1] << 16), (pk01[2] & 0xffffu) | (pk01[3] << 16)};
;           u32x2 w1 = {(pk01[0] >> 16) | (pk01[1] & 0xffff0000u), (pk01[2] >> 16) | (pk01[3] & 0xffff0000u)};
;           u32x2 w2 = {(pk23[0] & 0xffffu) | (pk23[1] << 16), (pk23[2] & 0xffffu) | (pk23[3] << 16)};
;           u32x2 w3 = {(pk23[0] >> 16) | (pk23[1] & 0xffff0000u), (pk23[2] >> 16) | (pk23[3] & 0xffff0000u)};
;           *reinterpret_cast<u32x2*>(t16 + (fq * 4 + 0) * (SEQ / 16)) = w0;
;           *reinterpret_cast<u32x2*>(t16 + (fq * 4 + 1) * (SEQ / 16)) = w1;
;           *reinterpret_cast<u32x2*>(t16 + (fq * 4 + 2) * (SEQ / 16)) = w2;
;           *reinterpret_cast<u32x2*>(t16 + (fq * 4 + 3) * (SEQ / 16)) = w3;
;     ...
;     __syncthreads();
	v_lshl_or_b32 v12, v84, 16, v12
	v_lshl_or_b32 v13, v66, 16, v13
	v_lshrrev_b32_e32 v16, 16, v82
	v_lshrrev_b32_e32 v17, 16, v74
	v_lshl_add_u64 v[8:9], v[8:9], 0, v[0:1]
	ds_write2_b64 v42, v[82:83], v[84:85] offset0:32 offset1:36
	ds_write2_b64 v42, v[74:75], v[66:67] offset0:40 offset1:44
	v_and_or_b32 v16, v84, s13, v16
	v_and_or_b32 v17, v66, s13, v17
	v_and_b32_e32 v20, 0xffff, v83
	v_and_b32_e32 v21, 0xffff, v75
	v_add_co_u32_e32 v8, vcc, s12, v8
	v_lshl_or_b32 v20, v85, 16, v20
	v_lshl_or_b32 v21, v67, 16, v21
	v_lshrrev_b32_e32 v28, 16, v83
	v_lshrrev_b32_e32 v29, 16, v75
	v_addc_co_u32_e32 v9, vcc, 0, v9, vcc
	v_and_or_b32 v28, v85, s13, v28
	v_and_or_b32 v29, v67, s13, v29
	v_or_b32_e32 v8, 0x80, v36
	v_lshl_add_u32 v34, v8, 9, v5
	v_lshlrev_b32_e32 v8, 15, v8
	v_mov_b32_e32 v9, v1
	v_lshl_add_u64 v[8:9], s[48:49], 0, v[8:9]
	v_lshl_add_u64 v[8:9], v[8:9], 0, s[50:51]
	v_lshl_add_u64 v[12:13], v[8:9], 0, s[44:45]
	v_and_b32_e32 v16, 0xffff, v62
	v_and_b32_e32 v17, 0xffff, v46
	v_lshl_or_b32 v16, v54, 16, v16
	v_lshl_or_b32 v17, v40, 16, v17
	v_lshrrev_b32_e32 v20, 16, v62
	v_lshrrev_b32_e32 v21, 16, v46
	v_lshl_add_u64 v[12:13], v[12:13], 0, v[0:1]
	ds_write2_b64 v34, v[62:63], v[54:55] offset1:4
	ds_write2_b64 v34, v[46:47], v[40:41] offset0:8 offset1:12
	v_and_or_b32 v20, v54, s13, v20
	v_and_or_b32 v21, v40, s13, v21
	v_and_b32_e32 v28, 0xffff, v63
	v_and_b32_e32 v29, 0xffff, v47
	v_add_co_u32_e32 v12, vcc, s12, v12
	v_lshl_or_b32 v28, v55, 16, v28
	v_lshl_or_b32 v29, v41, 16, v29
	v_lshrrev_b32_e32 v32, 16, v63
	v_lshrrev_b32_e32 v33, 16, v47
	v_addc_co_u32_e32 v13, vcc, 0, v13, vcc
	v_and_or_b32 v32, v55, s13, v32
	v_and_or_b32 v33, v41, s13, v33
	v_or_b32_e32 v12, 0x90, v36
	v_lshl_add_u32 v5, v12, 9, v5
	v_lshlrev_b32_e32 v12, 15, v12
	v_mov_b32_e32 v13, v1
	v_lshl_add_u64 v[12:13], s[48:49], 0, v[12:13]
	v_lshl_add_u64 v[12:13], v[12:13], 0, s[50:51]
	v_lshl_add_u64 v[16:17], v[12:13], 0, s[44:45]
	v_and_b32_e32 v20, 0xffff, v58
	v_and_b32_e32 v21, 0xffff, v38
	v_lshrrev_b32_e32 v29, 16, v38
	ds_write2_b64 v5, v[58:59], v[50:51] offset1:4
	ds_write2_b64 v5, v[38:39], v[30:31] offset0:8 offset1:12
	v_lshl_or_b32 v20, v50, 16, v20
	v_lshl_or_b32 v21, v30, 16, v21
	v_lshrrev_b32_e32 v28, 16, v58
	v_and_or_b32 v29, v30, s13, v29
	v_and_b32_e32 v30, 0xffff, v59
	v_lshl_add_u64 v[16:17], v[16:17], 0, v[0:1]
	v_and_or_b32 v28, v50, s13, v28
	v_lshl_or_b32 v32, v51, 16, v30
	v_and_b32_e32 v30, 0xffff, v39
	v_add_co_u32_e32 v16, vcc, s12, v16
	v_lshl_or_b32 v33, v31, 16, v30
	v_lshrrev_b32_e32 v30, 16, v59
	v_lshrrev_b32_e32 v35, 16, v39
	v_addc_co_u32_e32 v17, vcc, 0, v17, vcc
	v_and_or_b32 v30, v51, s13, v30
	v_and_or_b32 v31, v31, s13, v35
	ds_write2_b64 v34, v[24:25], v[26:27] offset0:32 offset1:36
	ds_write2_b64 v34, v[14:15], v[6:7] offset0:40 offset1:44
	v_lshl_add_u64 v[8:9], v[8:9], 0, s[46:47]
	v_and_b32_e32 v16, 0xffff, v24
	v_and_b32_e32 v17, 0xffff, v14
	v_lshrrev_b32_e32 v14, 16, v14
	v_lshl_or_b32 v16, v26, 16, v16
	v_lshl_or_b32 v17, v6, 16, v17
	v_lshrrev_b32_e32 v20, 16, v24
	v_and_or_b32 v21, v6, s13, v14
	v_and_b32_e32 v6, 0xffff, v25
	v_lshl_add_u64 v[8:9], v[8:9], 0, v[0:1]
	v_and_or_b32 v20, v26, s13, v20
	v_lshl_or_b32 v28, v27, 16, v6
	v_and_b32_e32 v6, 0xffff, v15
	v_add_co_u32_e32 v8, vcc, s12, v8
	v_lshl_or_b32 v29, v7, 16, v6
	v_lshrrev_b32_e32 v6, 16, v25
	v_lshrrev_b32_e32 v14, 16, v15
	v_addc_co_u32_e32 v9, vcc, 0, v9, vcc
	v_and_or_b32 v6, v27, s13, v6
	v_and_or_b32 v7, v7, s13, v14
	ds_write2_b64 v5, v[22:23], v[18:19] offset0:32 offset1:36
	ds_write2_b64 v5, v[10:11], v[2:3] offset0:40 offset1:44
	v_and_b32_e32 v5, 0xffff, v22
	v_lshl_or_b32 v8, v18, 16, v5
	v_and_b32_e32 v5, 0xffff, v10
	v_lshl_or_b32 v9, v2, 16, v5
	v_lshrrev_b32_e32 v5, 16, v22
	v_lshl_add_u64 v[6:7], v[12:13], 0, s[46:47]
	v_and_or_b32 v12, v18, s13, v5
	v_lshrrev_b32_e32 v5, 16, v10
	v_and_or_b32 v13, v2, s13, v5
	v_and_b32_e32 v2, 0xffff, v23
	v_lshl_or_b32 v14, v19, 16, v2
	v_and_b32_e32 v2, 0xffff, v11
	v_lshl_add_u64 v[6:7], v[6:7], 0, v[0:1]
	v_lshl_or_b32 v15, v3, 16, v2
	v_lshrrev_b32_e32 v2, 16, v23
	v_lshrrev_b32_e32 v5, 16, v11
	v_add_co_u32_e32 v6, vcc, s12, v6
	v_and_or_b32 v2, v19, s13, v2
	v_and_or_b32 v3, v3, s13, v5
	v_addc_co_u32_e32 v7, vcc, 0, v7, vcc
	v_bfe_u32 v0, v4, 3, 2
	v_and_b32_e32 v5, 7, v4
	v_lshlrev_b32_e32 v2, 6, v5
	v_lshlrev_b32_e32 v3, 1, v0
	v_add3_u32 v14, 16, v2, v3
	v_lshlrev_b32_e32 v0, 13, v0
	v_readlane_b32 s10, v255, 51
	v_ashrrev_i32_e32 v10, 5, v4
	v_lshl_add_u64 v[2:3], s[48:49], 0, v[0:1]
	s_lshl_b32 s10, s10, 6
	v_lshlrev_b32_e32 v0, 4, v5
	v_lshl_add_u32 v5, v10, 9, v14
	s_waitcnt vmcnt(62) lgkmcnt(0)
	s_barrier
; template <int TRM>
; DI void inproj_epi(const acc4 (&acc)[2][2][4][2], int wr, int wc, int fr, int fq, int pm, int pn, u16* R, u16* T, float* CB, u32* KMAX2, const float* bfp, char* lds) {
;     ...
;           const int p16 = (pm * 256 + ai * 128 + wr * 64) >> 4;
;           u16* t16 = T + (size_t)(TR_VB16 + cl) * SEQ + p16;
;           u32x2 w0 = {(pk01[0] & 0xffffu) | (pk01[1] << 16), (pk01[2] & 0xffffu) | (pk01[3] << 16)};
;           u32x2 w1 = {(pk01[0] >> 16) | (pk01[1] & 0xffff0000u), (pk01[2] >> 16) | (pk01[3] & 0xffff0000u)};
;           u32x2 w2 = {(pk23[0] & 0xffffu) | (pk23[1] << 16), (pk23[2] & 0xffffu) | (pk23[3] << 16)};
;           u32x2 w3 = {(pk23[0] >> 16) | (pk23[1] & 0xffff0000u), (pk23[2] >> 16) | (pk23[3] & 0xffff0000u)};
;           *reinterpret_cast<u32x2*>(t16 + (fq * 4 + 0) * (SEQ / 16)) = w0;
;           *reinterpret_cast<u32x2*>(t16 + (fq * 4 + 1) * (SEQ / 16)) = w1;
;           *reinterpret_cast<u32x2*>(t16 + (fq * 4 + 2) * (SEQ / 16)) = w2;
;           *reinterpret_cast<u32x2*>(t16 + (fq * 4 + 3) * (SEQ / 16)) = w3;
;     ...
;     for (int c = 0; c < 16; ++c) {
;       const int id = tx + 512 * c, cl = id >> 5, res = (id >> 3) & 3, ch = id & 7;
;       const u16* sp = sT + cl * 256 + 32 * ch + res;
;       u32 w[4];
; #pragma unroll
;       for (int e = 0; e < 4; ++e) w[e] = (u32)sp[8 * e] | ((u32)sp[8 * e + 4] << 16);
;       u32x4 o = {w[0], w[1], w[2], w[3]};
;       *reinterpret_cast<u32x4*>(T + (size_t)(TR_VB4 + cl) * SEQ + res * (SEQ / 4) + pm * 64 + 8 * ch) = o;
;     }
	v_lshrrev_b32_e32 v199, 5, v4
	v_lshlrev_b32_e32 v224, 9, v199
	v_lshlrev_b32_e32 v198, 15, v199
	v_bfe_u32 v199, v4, 1, 4
	v_lshl_add_u32 v224, v199, 1, v224
	v_lshl_add_u32 v198, v199, 11, v198
	v_and_b32_e32 v199, 1, v4
	v_lshl_add_u32 v224, v199, 8, v224
	v_lshl_add_u32 v198, v199, 4, v198
	v_add_u32_e32 v224, 16, v224
	v_add_u32_e32 v225, 0x10000, v224
	v_readlane_b32 s100, v255, 51
	s_lshl_b32 s100, s100, 5
	s_add_u32 s100, s48, s100
	s_addc_u32 s101, s49, 0
	s_add_u32 s100, s100, 0x2400000
	s_addc_u32 s101, s101, 0
	ds_read_u16 v200, v224
	ds_read_u16 v201, v224 offset:32
	ds_read_u16 v202, v224 offset:64
	ds_read_u16 v203, v224 offset:96
	ds_read_u16 v204, v224 offset:128
	ds_read_u16 v205, v224 offset:160
	ds_read_u16 v206, v224 offset:192
	ds_read_u16 v207, v224 offset:224
	ds_read_u16 v208, v224 offset:8192
	ds_read_u16 v209, v224 offset:8224
	ds_read_u16 v210, v224 offset:8256
	ds_read_u16 v211, v224 offset:8288
	ds_read_u16 v212, v224 offset:8320
	ds_read_u16 v213, v224 offset:8352
	ds_read_u16 v214, v224 offset:8384
	ds_read_u16 v215, v224 offset:8416
	s_waitcnt lgkmcnt(8)
	v_lshl_or_b32 v216, v201, 16, v200
	v_lshl_or_b32 v217, v203, 16, v202
	v_lshl_or_b32 v218, v205, 16, v204
	v_lshl_or_b32 v219, v207, 16, v206
	global_store_dwordx4 v198, v[216:219], s[100:101]
	s_add_u32 s100, s100, 0x80000
	s_addc_u32 s101, s101, 0
	ds_read_u16 v200, v224 offset:16384
	ds_read_u16 v201, v224 offset:16416
	ds_read_u16 v202, v224 offset:16448
	ds_read_u16 v203, v224 offset:16480
	ds_read_u16 v204, v224 offset:16512
	ds_read_u16 v205, v224 offset:16544
	ds_read_u16 v206, v224 offset:16576
	ds_read_u16 v207, v224 offset:16608
	s_waitcnt lgkmcnt(8)
	v_lshl_or_b32 v220, v209, 16, v208
	v_lshl_or_b32 v221, v211, 16, v210
	v_lshl_or_b32 v222, v213, 16, v212
	v_lshl_or_b32 v223, v215, 16, v214
	global_store_dwordx4 v198, v[220:223], s[100:101]
	s_add_u32 s100, s100, 0x80000
	s_addc_u32 s101, s101, 0
	ds_read_u16 v208, v224 offset:24576
	ds_read_u16 v209, v224 offset:24608
	ds_read_u16 v210, v224 offset:24640
	ds_read_u16 v211, v224 offset:24672
	ds_read_u16 v212, v224 offset:24704
	ds_read_u16 v213, v224 offset:24736
	ds_read_u16 v214, v224 offset:24768
	ds_read_u16 v215, v224 offset:24800
	s_waitcnt lgkmcnt(8)
	v_lshl_or_b32 v216, v201, 16, v200
	v_lshl_or_b32 v217, v203, 16, v202
	v_lshl_or_b32 v218, v205, 16, v204
	v_lshl_or_b32 v219, v207, 16, v206
	global_store_dwordx4 v198, v[216:219], s[100:101]
	s_add_u32 s100, s100, 0x80000
	s_addc_u32 s101, s101, 0
	ds_read_u16 v200, v224 offset:32768
	ds_read_u16 v201, v224 offset:32800
	ds_read_u16 v202, v224 offset:32832
	ds_read_u16 v203, v224 offset:32864
	ds_read_u16 v204, v224 offset:32896
	ds_read_u16 v205, v224 offset:32928
	ds_read_u16 v206, v224 offset:32960
	ds_read_u16 v207, v224 offset:32992
	s_waitcnt lgkmcnt(8)
	v_lshl_or_b32 v220, v209, 16, v208
	v_lshl_or_b32 v221, v211, 16, v210
	v_lshl_or_b32 v222, v213, 16, v212
	v_lshl_or_b32 v223, v215, 16, v214
	global_store_dwordx4 v198, v[220:223], s[100:101]
	s_add_u32 s100, s100, 0x80000
	s_addc_u32 s101, s101, 0
	ds_read_u16 v208, v224 offset:40960
	ds_read_u16 v209, v224 offset:40992
	ds_read_u16 v210, v224 offset:41024
	ds_read_u16 v211, v224 offset:41056
	ds_read_u16 v212, v224 offset:41088
	ds_read_u16 v213, v224 offset:41120
	ds_read_u16 v214, v224 offset:41152
	ds_read_u16 v215, v224 offset:41184
	s_waitcnt lgkmcnt(8)
	v_lshl_or_b32 v216, v201, 16, v200
	v_lshl_or_b32 v217, v203, 16, v202
	v_lshl_or_b32 v218, v205, 16, v204
	v_lshl_or_b32 v219, v207, 16, v206
	global_store_dwordx4 v198, v[216:219], s[100:101]
	s_add_u32 s100, s100, 0x80000
	s_addc_u32 s101, s101, 0
	ds_read_u16 v200, v224 offset:49152
	ds_read_u16 v201, v224 offset:49184
	ds_read_u16 v202, v224 offset:49216
	ds_read_u16 v203, v224 offset:49248
	ds_read_u16 v204, v224 offset:49280
	ds_read_u16 v205, v224 offset:49312
	ds_read_u16 v206, v224 offset:49344
	ds_read_u16 v207, v224 offset:49376
	s_waitcnt lgkmcnt(8)
	v_lshl_or_b32 v220, v209, 16, v208
	v_lshl_or_b32 v221, v211, 16, v210
	v_lshl_or_b32 v222, v213, 16, v212
	v_lshl_or_b32 v223, v215, 16, v214
	global_store_dwordx4 v198, v[220:223], s[100:101]
	s_add_u32 s100, s100, 0x80000
	s_addc_u32 s101, s101, 0
	ds_read_u16 v208, v224 offset:57344
	ds_read_u16 v209, v224 offset:57376
	ds_read_u16 v210, v224 offset:57408
	ds_read_u16 v211, v224 offset:57440
	ds_read_u16 v212, v224 offset:57472
	ds_read_u16 v213, v224 offset:57504
	ds_read_u16 v214, v224 offset:57536
	ds_read_u16 v215, v224 offset:57568
	s_waitcnt lgkmcnt(8)
	v_lshl_or_b32 v216, v201, 16, v200
	v_lshl_or_b32 v217, v203, 16, v202
	v_lshl_or_b32 v218, v205, 16, v204
	v_lshl_or_b32 v219, v207, 16, v206
	global_store_dwordx4 v198, v[216:219], s[100:101]
	s_add_u32 s100, s100, 0x80000
	s_addc_u32 s101, s101, 0
	ds_read_u16 v200, v225
	ds_read_u16 v201, v225 offset:32
	ds_read_u16 v202, v225 offset:64
	ds_read_u16 v203, v225 offset:96
	ds_read_u16 v204, v225 offset:128
	ds_read_u16 v205, v225 offset:160
	ds_read_u16 v206, v225 offset:192
	ds_read_u16 v207, v225 offset:224
	s_waitcnt lgkmcnt(8)
	v_lshl_or_b32 v220, v209, 16, v208
	v_lshl_or_b32 v221, v211, 16, v210
	v_lshl_or_b32 v222, v213, 16, v212
	v_lshl_or_b32 v223, v215, 16, v214
	global_store_dwordx4 v198, v[220:223], s[100:101]
	s_add_u32 s100, s100, 0x80000
	s_addc_u32 s101, s101, 0
	ds_read_u16 v208, v225 offset:8192
	ds_read_u16 v209, v225 offset:8224
	ds_read_u16 v210, v225 offset:8256
	ds_read_u16 v211, v225 offset:8288
	ds_read_u16 v212, v225 offset:8320
	ds_read_u16 v213, v225 offset:8352
	ds_read_u16 v214, v225 offset:8384
	ds_read_u16 v215, v225 offset:8416
	s_waitcnt lgkmcnt(8)
; template <int TRM>
; DI void inproj_epi(const acc4 (&acc)[2][2][4][2], int wr, int wc, int fr, int fq, int pm, int pn, u16* R, u16* T, float* CB, u32* KMAX2, const float* bfp, char* lds) {
;     ...
;           const int p16 = (pm * 256 + ai * 128 + wr * 64) >> 4;
;           u16* t16 = T + (size_t)(TR_VB16 + cl) * SEQ + p16;
;           u32x2 w0 = {(pk01[0] & 0xffffu) | (pk01[1] << 16), (pk01[2] & 0xffffu) | (pk01[3] << 16)};
;           u32x2 w1 = {(pk01[0] >> 16) | (pk01[1] & 0xffff0000u), (pk01[2] >> 16) | (pk01[3] & 0xffff0000u)};
;           u32x2 w2 = {(pk23[0] & 0xffffu) | (pk23[1] << 16), (pk23[2] & 0xffffu) | (pk23[3] << 16)};
;           u32x2 w3 = {(pk23[0] >> 16) | (pk23[1] & 0xffff0000u), (pk23[2] >> 16) | (pk23[3] & 0xffff0000u)};
;           *reinterpret_cast<u32x2*>(t16 + (fq * 4 + 0) * (SEQ / 16)) = w0;
;           *reinterpret_cast<u32x2*>(t16 + (fq * 4 + 1) * (SEQ / 16)) = w1;
;           *reinterpret_cast<u32x2*>(t16 + (fq * 4 + 2) * (SEQ / 16)) = w2;
;           *reinterpret_cast<u32x2*>(t16 + (fq * 4 + 3) * (SEQ / 16)) = w3;
;     ...
;     for (int c = 0; c < 16; ++c) {
;       const int id = tx + 512 * c, cl = id >> 5, res = (id >> 3) & 3, ch = id & 7;
;       const u16* sp = sT + cl * 256 + 32 * ch + res;
;       u32 w[4];
; #pragma unroll
;       for (int e = 0; e < 4; ++e) w[e] = (u32)sp[8 * e] | ((u32)sp[8 * e + 4] << 16);
;       u32x4 o = {w[0], w[1], w[2], w[3]};
;       *reinterpret_cast<u32x4*>(T + (size_t)(TR_VB4 + cl) * SEQ + res * (SEQ / 4) + pm * 64 + 8 * ch) = o;
;     }
	v_lshl_or_b32 v216, v201, 16, v200
	v_lshl_or_b32 v217, v203, 16, v202
	v_lshl_or_b32 v218, v205, 16, v204
	v_lshl_or_b32 v219, v207, 16, v206
	global_store_dwordx4 v198, v[216:219], s[100:101]
	s_add_u32 s100, s100, 0x80000
	s_addc_u32 s101, s101, 0
	ds_read_u16 v200, v225 offset:16384
	ds_read_u16 v201, v225 offset:16416
	ds_read_u16 v202, v225 offset:16448
	ds_read_u16 v203, v225 offset:16480
	ds_read_u16 v204, v225 offset:16512
	ds_read_u16 v205, v225 offset:16544
	ds_read_u16 v206, v225 offset:16576
	ds_read_u16 v207, v225 offset:16608
	s_waitcnt lgkmcnt(8)
	v_lshl_or_b32 v220, v209, 16, v208
	v_lshl_or_b32 v221, v211, 16, v210
	v_lshl_or_b32 v222, v213, 16, v212
	v_lshl_or_b32 v223, v215, 16, v214
	global_store_dwordx4 v198, v[220:223], s[100:101]
	s_add_u32 s100, s100, 0x80000
	s_addc_u32 s101, s101, 0
	ds_read_u16 v208, v225 offset:24576
	ds_read_u16 v209, v225 offset:24608
	ds_read_u16 v210, v225 offset:24640
	ds_read_u16 v211, v225 offset:24672
	ds_read_u16 v212, v225 offset:24704
	ds_read_u16 v213, v225 offset:24736
	ds_read_u16 v214, v225 offset:24768
	ds_read_u16 v215, v225 offset:24800
	s_waitcnt lgkmcnt(8)
	v_lshl_or_b32 v216, v201, 16, v200
	v_lshl_or_b32 v217, v203, 16, v202
	v_lshl_or_b32 v218, v205, 16, v204
	v_lshl_or_b32 v219, v207, 16, v206
	global_store_dwordx4 v198, v[216:219], s[100:101]
	s_add_u32 s100, s100, 0x80000
	s_addc_u32 s101, s101, 0
	ds_read_u16 v200, v225 offset:32768
	ds_read_u16 v201, v225 offset:32800
	ds_read_u16 v202, v225 offset:32832
	ds_read_u16 v203, v225 offset:32864
	ds_read_u16 v204, v225 offset:32896
	ds_read_u16 v205, v225 offset:32928
	ds_read_u16 v206, v225 offset:32960
	ds_read_u16 v207, v225 offset:32992
	s_waitcnt lgkmcnt(8)
	v_lshl_or_b32 v220, v209, 16, v208
	v_lshl_or_b32 v221, v211, 16, v210
	v_lshl_or_b32 v222, v213, 16, v212
	v_lshl_or_b32 v223, v215, 16, v214
	global_store_dwordx4 v198, v[220:223], s[100:101]
	s_add_u32 s100, s100, 0x80000
	s_addc_u32 s101, s101, 0
	ds_read_u16 v208, v225 offset:40960
	ds_read_u16 v209, v225 offset:40992
	ds_read_u16 v210, v225 offset:41024
	ds_read_u16 v211, v225 offset:41056
	ds_read_u16 v212, v225 offset:41088
	ds_read_u16 v213, v225 offset:41120
	ds_read_u16 v214, v225 offset:41152
	ds_read_u16 v215, v225 offset:41184
	s_waitcnt lgkmcnt(8)
	v_lshl_or_b32 v216, v201, 16, v200
	v_lshl_or_b32 v217, v203, 16, v202
	v_lshl_or_b32 v218, v205, 16, v204
	v_lshl_or_b32 v219, v207, 16, v206
	global_store_dwordx4 v198, v[216:219], s[100:101]
	s_add_u32 s100, s100, 0x80000
	s_addc_u32 s101, s101, 0
	ds_read_u16 v200, v225 offset:49152
	ds_read_u16 v201, v225 offset:49184
	ds_read_u16 v202, v225 offset:49216
	ds_read_u16 v203, v225 offset:49248
	ds_read_u16 v204, v225 offset:49280
	ds_read_u16 v205, v225 offset:49312
	ds_read_u16 v206, v225 offset:49344
	ds_read_u16 v207, v225 offset:49376
	s_waitcnt lgkmcnt(8)
	v_lshl_or_b32 v220, v209, 16, v208
	v_lshl_or_b32 v221, v211, 16, v210
	v_lshl_or_b32 v222, v213, 16, v212
	v_lshl_or_b32 v223, v215, 16, v214
	global_store_dwordx4 v198, v[220:223], s[100:101]
	s_add_u32 s100, s100, 0x80000
	s_addc_u32 s101, s101, 0
	ds_read_u16 v208, v225 offset:57344
	ds_read_u16 v209, v225 offset:57376
	ds_read_u16 v210, v225 offset:57408
	ds_read_u16 v211, v225 offset:57440
	ds_read_u16 v212, v225 offset:57472
	ds_read_u16 v213, v225 offset:57504
	ds_read_u16 v214, v225 offset:57536
	ds_read_u16 v215, v225 offset:57568
	s_waitcnt lgkmcnt(8)
	v_lshl_or_b32 v216, v201, 16, v200
	v_lshl_or_b32 v217, v203, 16, v202
	v_lshl_or_b32 v218, v205, 16, v204
	v_lshl_or_b32 v219, v207, 16, v206
	global_store_dwordx4 v198, v[216:219], s[100:101]
	s_add_u32 s100, s100, 0x80000
	s_addc_u32 s101, s101, 0
	s_waitcnt lgkmcnt(0)
	v_lshl_or_b32 v220, v209, 16, v208
	v_lshl_or_b32 v221, v211, 16, v210
	v_lshl_or_b32 v222, v213, 16, v212
	v_lshl_or_b32 v223, v215, 16, v214
	global_store_dwordx4 v198, v[220:223], s[100:101]
	s_ashr_i32 s11, s10, 31
	ds_read_u16 v6, v5
	ds_read_u16 v7, v5 offset:8
	ds_read_u16 v8, v5 offset:16
	ds_read_u16 v9, v5 offset:24
	ds_read_u16 v11, v5 offset:32
	ds_read_u16 v12, v5 offset:40
	ds_read_u16 v13, v5 offset:48
	ds_read_u16 v5, v5 offset:56
	v_lshl_add_u64 v[2:3], s[10:11], 1, v[2:3]
	v_lshl_add_u64 v[2:3], v[2:3], 0, v[0:1]
	v_add_u32_e32 v0, 0x200, v4
	s_waitcnt lgkmcnt(6)
	v_lshl_or_b32 v6, v7, 16, v6
	s_waitcnt lgkmcnt(4)
	v_lshl_or_b32 v7, v9, 16, v8
	s_waitcnt lgkmcnt(2)
	v_lshl_or_b32 v8, v12, 16, v11
	v_ashrrev_i32_e32 v12, 5, v0
	v_lshl_add_u32 v0, v12, 9, v14
	s_waitcnt lgkmcnt(0)
	v_lshl_or_b32 v9, v5, 16, v13
	v_ashrrev_i32_e32 v11, 31, v10
	ds_read_u16 v5, v0
	ds_read_u16 v13, v0 offset:8
	ds_read_u16 v15, v0 offset:16
	ds_read_u16 v16, v0 offset:24
	ds_read_u16 v17, v0 offset:32
	ds_read_u16 v18, v0 offset:40
	ds_read_u16 v19, v0 offset:48
	ds_read_u16 v0, v0 offset:56
	v_lshlrev_b64 v[10:11], 15, v[10:11]
	v_lshl_add_u64 v[10:11], v[2:3], 0, v[10:11]
	s_mov_b32 s10, 0x1c00000
	v_add_co_u32_e32 v10, vcc, s10, v10
	s_nop 1
	v_addc_co_u32_e32 v11, vcc, 0, v11, vcc
	global_store_dwordx4 v[10:11], v[6:9], off
	s_waitcnt lgkmcnt(6)
	s_nop 0
	v_lshl_or_b32 v6, v13, 16, v5
	s_waitcnt lgkmcnt(0)
	v_lshl_or_b32 v9, v0, 16, v19
	v_ashrrev_i32_e32 v13, 31, v12
	v_add_u32_e32 v0, 0x400, v4
	v_lshlrev_b64 v[10:11], 15, v[12:13]
	v_ashrrev_i32_e32 v12, 5, v0
	v_lshl_add_u32 v0, v12, 9, v14
	v_lshl_or_b32 v7, v16, 16, v15
	v_lshl_or_b32 v8, v18, 16, v17
	ds_read_u16 v5, v0
	ds_read_u16 v13, v0 offset:8
	ds_read_u16 v15, v0 offset:16
	ds_read_u16 v16, v0 offset:24
	ds_read_u16 v17, v0 offset:32
	ds_read_u16 v18, v0 offset:40
	ds_read_u16 v19, v0 offset:48
	ds_read_u16 v0, v0 offset:56
	v_lshl_add_u64 v[10:11], v[2:3], 0, v[10:11]
	v_add_co_u32_e32 v10, vcc, s10, v10
	s_nop 1
	v_addc_co_u32_e32 v11, vcc, 0, v11, vcc
	global_store_dwordx4 v[10:11], v[6:9], off
	s_waitcnt lgkmcnt(6)
; template <int TRM>
; DI void inproj_epi(const acc4 (&acc)[2][2][4][2], int wr, int wc, int fr, int fq, int pm, int pn, u16* R, u16* T, float* CB, u32* KMAX2, const float* bfp, char* lds) {
;     ...
;     for (int c = 0; c < 16; ++c) {
;       const int id = tx + 512 * c, cl = id >> 5, res = (id >> 3) & 3, ch = id & 7;
;       const u16* sp = sT + cl * 256 + 32 * ch + res;
;       u32 w[4];
; #pragma unroll
;       for (int e = 0; e < 4; ++e) w[e] = (u32)sp[8 * e] | ((u32)sp[8 * e + 4] << 16);
;       u32x4 o = {w[0], w[1], w[2], w[3]};
;       *reinterpret_cast<u32x4*>(T + (size_t)(TR_VB4 + cl) * SEQ + res * (SEQ / 4) + pm * 64 + 8 * ch) = o;
;     }
	s_nop 0
	v_lshl_or_b32 v6, v13, 16, v5
	s_waitcnt lgkmcnt(0)
	v_lshl_or_b32 v9, v0, 16, v19
	v_ashrrev_i32_e32 v13, 31, v12
	v_add_u32_e32 v0, 0x600, v4
	v_lshlrev_b64 v[10:11], 15, v[12:13]
	v_ashrrev_i32_e32 v12, 5, v0
	v_lshl_add_u32 v0, v12, 9, v14
	v_lshl_or_b32 v7, v16, 16, v15
	v_lshl_or_b32 v8, v18, 16, v17
	ds_read_u16 v5, v0
	ds_read_u16 v13, v0 offset:8
	ds_read_u16 v15, v0 offset:16
	ds_read_u16 v16, v0 offset:24
	ds_read_u16 v17, v0 offset:32
	ds_read_u16 v18, v0 offset:40
	ds_read_u16 v19, v0 offset:48
	ds_read_u16 v0, v0 offset:56
	v_lshl_add_u64 v[10:11], v[2:3], 0, v[10:11]
	v_add_co_u32_e32 v10, vcc, s10, v10
	s_nop 1
	v_addc_co_u32_e32 v11, vcc, 0, v11, vcc
	global_store_dwordx4 v[10:11], v[6:9], off
	s_waitcnt lgkmcnt(6)
	s_nop 0
	v_lshl_or_b32 v6, v13, 16, v5
	s_waitcnt lgkmcnt(0)
	v_lshl_or_b32 v9, v0, 16, v19
	v_ashrrev_i32_e32 v13, 31, v12
	v_add_u32_e32 v0, 0x800, v4
	v_lshlrev_b64 v[10:11], 15, v[12:13]
	v_ashrrev_i32_e32 v12, 5, v0
	v_lshl_add_u32 v0, v12, 9, v14
	v_lshl_or_b32 v7, v16, 16, v15
	v_lshl_or_b32 v8, v18, 16, v17
	ds_read_u16 v5, v0
	ds_read_u16 v13, v0 offset:8
	ds_read_u16 v15, v0 offset:16
	ds_read_u16 v16, v0 offset:24
	ds_read_u16 v17, v0 offset:32
	ds_read_u16 v18, v0 offset:40
	ds_read_u16 v19, v0 offset:48
	ds_read_u16 v0, v0 offset:56
	v_lshl_add_u64 v[10:11], v[2:3], 0, v[10:11]
	v_add_co_u32_e32 v10, vcc, s10, v10
	s_nop 1
	v_addc_co_u32_e32 v11, vcc, 0, v11, vcc
	global_store_dwordx4 v[10:11], v[6:9], off
	s_waitcnt lgkmcnt(6)
	s_nop 0
	v_lshl_or_b32 v6, v13, 16, v5
	s_waitcnt lgkmcnt(0)
	v_lshl_or_b32 v9, v0, 16, v19
	v_ashrrev_i32_e32 v13, 31, v12
	v_add_u32_e32 v0, 0xa00, v4
	v_lshlrev_b64 v[10:11], 15, v[12:13]
	v_ashrrev_i32_e32 v12, 5, v0
	v_lshl_add_u32 v0, v12, 9, v14
	v_lshl_or_b32 v7, v16, 16, v15
	v_lshl_or_b32 v8, v18, 16, v17
	ds_read_u16 v5, v0
	ds_read_u16 v13, v0 offset:8
	ds_read_u16 v15, v0 offset:16
	ds_read_u16 v16, v0 offset:24
	ds_read_u16 v17, v0 offset:32
	ds_read_u16 v18, v0 offset:40
	ds_read_u16 v19, v0 offset:48
	ds_read_u16 v0, v0 offset:56
	v_lshl_add_u64 v[10:11], v[2:3], 0, v[10:11]
	v_add_co_u32_e32 v10, vcc, s10, v10
	s_nop 1
	v_addc_co_u32_e32 v11, vcc, 0, v11, vcc
	global_store_dwordx4 v[10:11], v[6:9], off
	s_waitcnt lgkmcnt(6)
	s_nop 0
	v_lshl_or_b32 v6, v13, 16, v5
	s_waitcnt lgkmcnt(0)
	v_lshl_or_b32 v9, v0, 16, v19
	v_ashrrev_i32_e32 v13, 31, v12
	v_add_u32_e32 v0, 0xc00, v4
	v_lshlrev_b64 v[10:11], 15, v[12:13]
	v_ashrrev_i32_e32 v12, 5, v0
	v_lshl_add_u32 v0, v12, 9, v14
	v_lshl_or_b32 v7, v16, 16, v15
	v_lshl_or_b32 v8, v18, 16, v17
	ds_read_u16 v5, v0
	ds_read_u16 v13, v0 offset:8
	ds_read_u16 v15, v0 offset:16
	ds_read_u16 v16, v0 offset:24
	ds_read_u16 v17, v0 offset:32
	ds_read_u16 v18, v0 offset:40
	ds_read_u16 v19, v0 offset:48
	ds_read_u16 v0, v0 offset:56
	v_lshl_add_u64 v[10:11], v[2:3], 0, v[10:11]
	v_add_co_u32_e32 v10, vcc, s10, v10
	s_nop 1
	v_addc_co_u32_e32 v11, vcc, 0, v11, vcc
	global_store_dwordx4 v[10:11], v[6:9], off
	s_waitcnt lgkmcnt(6)
	s_nop 0
	v_lshl_or_b32 v6, v13, 16, v5
	s_waitcnt lgkmcnt(0)
	v_lshl_or_b32 v9, v0, 16, v19
	v_ashrrev_i32_e32 v13, 31, v12
	v_add_u32_e32 v0, 0xe00, v4
	v_lshlrev_b64 v[10:11], 15, v[12:13]
	v_ashrrev_i32_e32 v12, 5, v0
	v_lshl_add_u32 v0, v12, 9, v14
	v_lshl_or_b32 v7, v16, 16, v15
	v_lshl_or_b32 v8, v18, 16, v17
	ds_read_u16 v5, v0
	ds_read_u16 v13, v0 offset:8
	ds_read_u16 v15, v0 offset:16
	ds_read_u16 v16, v0 offset:24
	ds_read_u16 v17, v0 offset:32
	ds_read_u16 v18, v0 offset:40
	ds_read_u16 v19, v0 offset:48
	ds_read_u16 v0, v0 offset:56
	v_lshl_add_u64 v[10:11], v[2:3], 0, v[10:11]
	v_add_co_u32_e32 v10, vcc, s10, v10
	s_nop 1
	v_addc_co_u32_e32 v11, vcc, 0, v11, vcc
	global_store_dwordx4 v[10:11], v[6:9], off
	s_waitcnt lgkmcnt(6)
	s_nop 0
	v_lshl_or_b32 v6, v13, 16, v5
	s_waitcnt lgkmcnt(0)
	v_lshl_or_b32 v9, v0, 16, v19
	v_ashrrev_i32_e32 v13, 31, v12
	v_add_u32_e32 v0, 0x1000, v4
	v_lshlrev_b64 v[10:11], 15, v[12:13]
	v_ashrrev_i32_e32 v12, 5, v0
	v_lshl_add_u32 v0, v12, 9, v14
	v_lshl_or_b32 v7, v16, 16, v15
	v_lshl_or_b32 v8, v18, 16, v17
	ds_read_u16 v5, v0
	ds_read_u16 v13, v0 offset:8
	ds_read_u16 v15, v0 offset:16
	ds_read_u16 v16, v0 offset:24
	ds_read_u16 v17, v0 offset:32
	ds_read_u16 v18, v0 offset:40
	ds_read_u16 v19, v0 offset:48
	ds_read_u16 v0, v0 offset:56
	v_lshl_add_u64 v[10:11], v[2:3], 0, v[10:11]
	v_add_co_u32_e32 v10, vcc, s10, v10
	s_nop 1
	v_addc_co_u32_e32 v11, vcc, 0, v11, vcc
	global_store_dwordx4 v[10:11], v[6:9], off
	s_waitcnt lgkmcnt(6)
	s_nop 0
	v_lshl_or_b32 v6, v13, 16, v5
	s_waitcnt lgkmcnt(0)
	v_lshl_or_b32 v9, v0, 16, v19
	v_ashrrev_i32_e32 v13, 31, v12
	v_add_u32_e32 v0, 0x1200, v4
	v_lshlrev_b64 v[10:11], 15, v[12:13]
	v_ashrrev_i32_e32 v12, 5, v0
	v_lshl_add_u32 v0, v12, 9, v14
	v_lshl_or_b32 v7, v16, 16, v15
	v_lshl_or_b32 v8, v18, 16, v17
	ds_read_u16 v5, v0
	ds_read_u16 v13, v0 offset:8
	ds_read_u16 v15, v0 offset:16
	ds_read_u16 v16, v0 offset:24
	ds_read_u16 v17, v0 offset:32
	ds_read_u16 v18, v0 offset:40
	ds_read_u16 v19, v0 offset:48
	ds_read_u16 v0, v0 offset:56
	v_lshl_add_u64 v[10:11], v[2:3], 0, v[10:11]
	v_add_co_u32_e32 v10, vcc, s10, v10
	s_nop 1
	v_addc_co_u32_e32 v11, vcc, 0, v11, vcc
	global_store_dwordx4 v[10:11], v[6:9], off
	s_waitcnt lgkmcnt(6)
; template <int TRM>
; DI void inproj_epi(const acc4 (&acc)[2][2][4][2], int wr, int wc, int fr, int fq, int pm, int pn, u16* R, u16* T, float* CB, u32* KMAX2, const float* bfp, char* lds) {
;     ...
;     for (int c = 0; c < 16; ++c) {
;       const int id = tx + 512 * c, cl = id >> 5, res = (id >> 3) & 3, ch = id & 7;
;       const u16* sp = sT + cl * 256 + 32 * ch + res;
;       u32 w[4];
; #pragma unroll
;       for (int e = 0; e < 4; ++e) w[e] = (u32)sp[8 * e] | ((u32)sp[8 * e + 4] << 16);
;       u32x4 o = {w[0], w[1], w[2], w[3]};
;       *reinterpret_cast<u32x4*>(T + (size_t)(TR_VB4 + cl) * SEQ + res * (SEQ / 4) + pm * 64 + 8 * ch) = o;
;     }
;     __syncthreads();
	s_nop 0
	v_lshl_or_b32 v6, v13, 16, v5
	s_waitcnt lgkmcnt(0)
	v_lshl_or_b32 v9, v0, 16, v19
	v_ashrrev_i32_e32 v13, 31, v12
	v_add_u32_e32 v0, 0x1400, v4
	v_lshlrev_b64 v[10:11], 15, v[12:13]
	v_ashrrev_i32_e32 v12, 5, v0
	v_lshl_add_u32 v0, v12, 9, v14
	v_lshl_or_b32 v7, v16, 16, v15
	v_lshl_or_b32 v8, v18, 16, v17
	ds_read_u16 v5, v0
	ds_read_u16 v13, v0 offset:8
	ds_read_u16 v15, v0 offset:16
	ds_read_u16 v16, v0 offset:24
	ds_read_u16 v17, v0 offset:32
	ds_read_u16 v18, v0 offset:40
	ds_read_u16 v19, v0 offset:48
	ds_read_u16 v0, v0 offset:56
	v_lshl_add_u64 v[10:11], v[2:3], 0, v[10:11]
	v_add_co_u32_e32 v10, vcc, s10, v10
	s_nop 1
	v_addc_co_u32_e32 v11, vcc, 0, v11, vcc
	global_store_dwordx4 v[10:11], v[6:9], off
	s_waitcnt lgkmcnt(6)
	s_nop 0
	v_lshl_or_b32 v6, v13, 16, v5
	s_waitcnt lgkmcnt(0)
	v_lshl_or_b32 v9, v0, 16, v19
	v_ashrrev_i32_e32 v13, 31, v12
	v_add_u32_e32 v0, 0x1600, v4
	v_lshlrev_b64 v[10:11], 15, v[12:13]
	v_ashrrev_i32_e32 v12, 5, v0
	v_lshl_add_u32 v0, v12, 9, v14
	v_lshl_or_b32 v7, v16, 16, v15
	v_lshl_or_b32 v8, v18, 16, v17
	ds_read_u16 v5, v0
	ds_read_u16 v13, v0 offset:8
	ds_read_u16 v15, v0 offset:16
	ds_read_u16 v16, v0 offset:24
	ds_read_u16 v17, v0 offset:32
	ds_read_u16 v18, v0 offset:40
	ds_read_u16 v19, v0 offset:48
	ds_read_u16 v0, v0 offset:56
	v_lshl_add_u64 v[10:11], v[2:3], 0, v[10:11]
	v_add_co_u32_e32 v10, vcc, s10, v10
	s_nop 1
	v_addc_co_u32_e32 v11, vcc, 0, v11, vcc
	global_store_dwordx4 v[10:11], v[6:9], off
	s_waitcnt lgkmcnt(6)
	s_nop 0
	v_lshl_or_b32 v6, v13, 16, v5
	s_waitcnt lgkmcnt(0)
	v_lshl_or_b32 v9, v0, 16, v19
	v_ashrrev_i32_e32 v13, 31, v12
	v_add_u32_e32 v0, 0x1800, v4
	v_lshlrev_b64 v[10:11], 15, v[12:13]
	v_ashrrev_i32_e32 v12, 5, v0
	v_lshl_add_u32 v0, v12, 9, v14
	v_lshl_or_b32 v7, v16, 16, v15
	v_lshl_or_b32 v8, v18, 16, v17
	ds_read_u16 v5, v0
	ds_read_u16 v13, v0 offset:8
	ds_read_u16 v15, v0 offset:16
	ds_read_u16 v16, v0 offset:24
	ds_read_u16 v17, v0 offset:32
	ds_read_u16 v18, v0 offset:40
	ds_read_u16 v19, v0 offset:48
	ds_read_u16 v0, v0 offset:56
	v_lshl_add_u64 v[10:11], v[2:3], 0, v[10:11]
	v_add_co_u32_e32 v10, vcc, s10, v10
	s_nop 1
	v_addc_co_u32_e32 v11, vcc, 0, v11, vcc
	global_store_dwordx4 v[10:11], v[6:9], off
	s_waitcnt lgkmcnt(6)
	s_nop 0
	v_lshl_or_b32 v6, v13, 16, v5
	s_waitcnt lgkmcnt(0)
	v_lshl_or_b32 v9, v0, 16, v19
	v_ashrrev_i32_e32 v13, 31, v12
	v_add_u32_e32 v0, 0x1a00, v4
	v_lshlrev_b64 v[10:11], 15, v[12:13]
	v_ashrrev_i32_e32 v12, 5, v0
	v_lshl_add_u32 v0, v12, 9, v14
	v_lshl_or_b32 v7, v16, 16, v15
	v_lshl_or_b32 v8, v18, 16, v17
	ds_read_u16 v5, v0
	ds_read_u16 v13, v0 offset:8
	ds_read_u16 v15, v0 offset:16
	ds_read_u16 v16, v0 offset:24
	ds_read_u16 v17, v0 offset:32
	ds_read_u16 v18, v0 offset:40
	ds_read_u16 v19, v0 offset:48
	ds_read_u16 v0, v0 offset:56
	v_lshl_add_u64 v[10:11], v[2:3], 0, v[10:11]
	v_add_co_u32_e32 v10, vcc, s10, v10
	s_nop 1
	v_addc_co_u32_e32 v11, vcc, 0, v11, vcc
	global_store_dwordx4 v[10:11], v[6:9], off
	s_waitcnt lgkmcnt(6)
	s_nop 0
	v_lshl_or_b32 v6, v13, 16, v5
	s_waitcnt lgkmcnt(0)
	v_lshl_or_b32 v9, v0, 16, v19
	v_ashrrev_i32_e32 v13, 31, v12
	v_add_u32_e32 v0, 0x1c00, v4
	v_lshlrev_b64 v[10:11], 15, v[12:13]
	v_ashrrev_i32_e32 v12, 5, v0
	v_lshl_add_u32 v0, v12, 9, v14
	v_lshl_or_b32 v7, v16, 16, v15
	v_lshl_or_b32 v8, v18, 16, v17
	ds_read_u16 v5, v0
	ds_read_u16 v13, v0 offset:8
	ds_read_u16 v15, v0 offset:16
	ds_read_u16 v16, v0 offset:24
	ds_read_u16 v17, v0 offset:32
	ds_read_u16 v18, v0 offset:40
	ds_read_u16 v19, v0 offset:48
	ds_read_u16 v0, v0 offset:56
	v_lshl_add_u64 v[10:11], v[2:3], 0, v[10:11]
	v_add_co_u32_e32 v10, vcc, s10, v10
	s_nop 1
	v_addc_co_u32_e32 v11, vcc, 0, v11, vcc
	global_store_dwordx4 v[10:11], v[6:9], off
	s_waitcnt lgkmcnt(6)
	s_nop 0
	v_lshl_or_b32 v6, v13, 16, v5
	s_waitcnt lgkmcnt(0)
	v_lshl_or_b32 v9, v0, 16, v19
	v_ashrrev_i32_e32 v13, 31, v12
	v_add_u32_e32 v0, 0x1e00, v4
	v_lshlrev_b64 v[10:11], 15, v[12:13]
	v_ashrrev_i32_e32 v12, 5, v0
	v_lshl_add_u64 v[10:11], v[2:3], 0, v[10:11]
	v_lshl_add_u32 v0, v12, 9, v14
	v_lshl_or_b32 v7, v16, 16, v15
	v_lshl_or_b32 v8, v18, 16, v17
	v_add_co_u32_e32 v10, vcc, s10, v10
	ds_read_u16 v4, v0
	ds_read_u16 v5, v0 offset:8
	ds_read_u16 v13, v0 offset:16
	ds_read_u16 v14, v0 offset:24
	ds_read_u16 v15, v0 offset:32
	ds_read_u16 v16, v0 offset:40
	ds_read_u16 v17, v0 offset:48
	ds_read_u16 v0, v0 offset:56
	v_addc_co_u32_e32 v11, vcc, 0, v11, vcc
	s_waitcnt lgkmcnt(6)
	v_lshl_or_b32 v4, v5, 16, v4
	s_waitcnt lgkmcnt(4)
	v_lshl_or_b32 v5, v14, 16, v13
	v_ashrrev_i32_e32 v13, 31, v12
	global_store_dwordx4 v[10:11], v[6:9], off
	s_nop 1
	v_lshlrev_b64 v[8:9], 15, v[12:13]
	v_lshl_add_u64 v[2:3], v[2:3], 0, v[8:9]
	v_add_co_u32_e32 v2, vcc, 0x1c00000, v2
	s_waitcnt lgkmcnt(2)
	v_lshl_or_b32 v6, v16, 16, v15
	s_waitcnt lgkmcnt(0)
	v_lshl_or_b32 v7, v0, 16, v17
	v_addc_co_u32_e32 v3, vcc, 0, v3, vcc
	global_store_dwordx4 v[2:3], v[4:7], off
	s_waitcnt vmcnt(63) expcnt(7) lgkmcnt(15)
	s_barrier
